# static priority raise mirrored: one s_setprio 1 at kernel entry for waves 0-3
# speedup vs baseline: 1.0007x; 1.0007x over previous
; __global__ void __launch_bounds__(512, 2) mk_fwd(Args args) {
;     ...
;     F.tid = threadIdx.x; F.wave = __builtin_amdgcn_readfirstlane(F.tid >> 6);
;     F.G = gridDim.x; { const int bx = blockIdx.x; F.vcu = (F.G % 8 == 0) ? (bx % 8) * (F.G / 8) + bx / 8 : bx; }
.LBB0_8:
	s_or_b64 exec, exec, s[2:3]
	s_load_dwordx2 s[72:73], s[0:1], 0xc0
	s_lshr_b32 s68, s70, 6
	s_cmp_gt_u32 s68, 3
	s_cbranch_scc1 .Lmy_prio_done
	s_setprio 1
